# v26 + pass B: V-next chunk load issued at loop top (full iteration of cover) instead of right before the PV MFMAs
# speedup vs baseline: 1.0040x; 1.0040x over previous
; #define LAS __attribute__((address_space(3)))
; #define MFMA32(a, b, c) __builtin_amdgcn_mfma_f32_32x32x16_bf16((a), (b), (c), 0, 0, 0)
; __device__ __forceinline__ s16x4 vtr(const LAS unsigned char* p) { return __builtin_bit_cast(s16x4, __builtin_amdgcn_ds_read_tr16_b64_v4i16((LAS s16x4*)p)); }
; __device__ __forceinline__ void pv_chunk(f32x16 (&ot)[4], const LAS unsigned char* vtb, bf16x8 pf0, bf16x8 pf1) {
; #pragma unroll
;     for (int db = 0; db < 4; ++db)
; #pragma unroll
;         for (int s = 0; s < 2; ++s) {
;             const s16x4 a = vtr(vtb + (16 * s) * VROWB + 64 * db), b2 = vtr(vtb + (16 * s + 8) * VROWB + 64 * db);
;             const bf16x8 vf = (bf16x8){a[0], a[1], a[2], a[3], b2[0], b2[1], b2[2], b2[3]};
;             __builtin_amdgcn_s_setprio(1); ot[db] = MFMA32(vf, s ? pf1 : pf0, ot[db]); __builtin_amdgcn_s_setprio(0);
;         }
; __device__ __forceinline__ void diff_task(const bf16_t* proj, bf16_t* xo, int b, int h, int qb, float lam, float post, const float* g_diff, int  , LAS unsigned char* vl) {
;     ...
;         const float e0 = m0 - sh, e1 = m1 - sh;
;         float p[16];
; #pragma unroll
;         for (int r = 0; r < 16; ++r) { const float bq0 = B0(r) - e0, bq1 = B0(r) - e1; p[r] = __builtin_amdgcn_exp2f(s0[r] * c1 + bq0) * i0 - __builtin_amdgcn_exp2f(s1[r] * c1 + bq1) * i1; }
;         bf16x8 pf0 = pack8(p), pf1 = pack8(p + 8);
;         asm volatile("" : "+v"(pf0), "+v"(pf1));
;         load_v(vr, vcol + (size_t)(kn * 32) * NIN, 1, voff);
;         pv_chunk(ot, vtb, pf0, pf1);
;         store_k(kl, kr, lane);
;         store_v(vl, vr, lane);
;         sh += c2s;
;     }
.LBB0_325:
	ds_read_b64_tr_b16 v[134:135], v232
	ds_read_b64_tr_b16 v[136:137], v232 offset:2560
	ds_read_b64_tr_b16 v[138:139], v232 offset:5120
	ds_read_b64_tr_b16 v[140:141], v232 offset:7680
	ds_read_b64_tr_b16 v[142:143], v232 offset:64
	ds_read_b64_tr_b16 v[144:145], v232 offset:2624
	ds_read_b64_tr_b16 v[146:147], v232 offset:5184
	ds_read_b64_tr_b16 v[148:149], v232 offset:7744
	ds_read_b64_tr_b16 v[150:151], v232 offset:128
	ds_read_b64_tr_b16 v[152:153], v232 offset:2688
	v_sub_f32_e32 v186, v229, v231
	v_sub_f32_e32 v187, v230, v231
	v_sub_f32_e32 v184, v206, v186
	v_sub_f32_e32 v185, v206, v187
	v_fmac_f32_e32 v184, 0x3e38aa3b, v82
	v_fmac_f32_e32 v185, 0x3e38aa3b, v66
	v_exp_f32_e32 v184, v184
	v_exp_f32_e32 v185, v185
	v_sub_f32_e32 v82, v207, v187
	v_sub_f32_e32 v66, v207, v186
	v_fmac_f32_e32 v82, 0x3e38aa3b, v67
	v_fmac_f32_e32 v66, 0x3e38aa3b, v83
	v_exp_f32_e32 v67, v82
	v_pk_mul_f32 v[82:83], v[224:225], v[184:185]
	v_exp_f32_e32 v66, v66
	v_sub_f32_e32 v184, v82, v83
	v_sub_f32_e32 v82, v208, v186
	v_sub_f32_e32 v83, v208, v187
	v_fmac_f32_e32 v82, 0x3e38aa3b, v84
	v_fmac_f32_e32 v83, 0x3e38aa3b, v68
	v_sub_f32_e32 v68, v209, v186
	v_sub_f32_e32 v84, v209, v187
	v_exp_f32_e32 v82, v82
	v_exp_f32_e32 v83, v83
	v_fmac_f32_e32 v68, 0x3e38aa3b, v85
	v_fmac_f32_e32 v84, 0x3e38aa3b, v69
	v_exp_f32_e32 v68, v68
	v_exp_f32_e32 v69, v84
	v_pk_mul_f32 v[66:67], v[224:225], v[66:67]
	s_nop 0
	v_sub_f32_e32 v84, v66, v67
	v_pk_mul_f32 v[66:67], v[224:225], v[82:83]
	v_sub_f32_e32 v83, v211, v187
	v_sub_f32_e32 v82, v66, v67
	v_pk_mul_f32 v[66:67], v[224:225], v[68:69]
	v_sub_f32_e32 v68, v210, v186
	v_sub_f32_e32 v69, v210, v187
	v_fmac_f32_e32 v68, 0x3e38aa3b, v86
	v_fmac_f32_e32 v69, 0x3e38aa3b, v70
	v_sub_f32_e32 v70, v211, v186
	v_exp_f32_e32 v68, v68
	v_exp_f32_e32 v69, v69
	v_fmac_f32_e32 v70, 0x3e38aa3b, v87
	v_fmac_f32_e32 v83, 0x3e38aa3b, v71
	v_exp_f32_e32 v70, v70
	v_exp_f32_e32 v71, v83
	v_sub_f32_e32 v83, v66, v67
	v_pk_mul_f32 v[66:67], v[224:225], v[68:69]
	v_sub_f32_e32 v68, v212, v186
	v_sub_f32_e32 v69, v212, v187
	v_sub_f32_e32 v85, v66, v67
	v_pk_mul_f32 v[66:67], v[224:225], v[70:71]
	v_fmac_f32_e32 v68, 0x3e38aa3b, v88
	v_fmac_f32_e32 v69, 0x3e38aa3b, v72
	v_sub_f32_e32 v70, v213, v186
	v_sub_f32_e32 v71, v213, v187
	v_exp_f32_e32 v68, v68
	v_exp_f32_e32 v69, v69
	v_fmac_f32_e32 v70, 0x3e38aa3b, v89
	v_fmac_f32_e32 v71, 0x3e38aa3b, v73
	v_exp_f32_e32 v70, v70
	v_exp_f32_e32 v71, v71
	v_sub_f32_e32 v72, v66, v67
	v_pk_mul_f32 v[66:67], v[224:225], v[68:69]
	v_sub_f32_e32 v68, v214, v186
	v_sub_f32_e32 v69, v214, v187
	v_sub_f32_e32 v73, v66, v67
	v_pk_mul_f32 v[66:67], v[224:225], v[70:71]
	v_fmac_f32_e32 v68, 0x3e38aa3b, v90
	v_fmac_f32_e32 v69, 0x3e38aa3b, v74
	v_sub_f32_e32 v70, v215, v186
	v_sub_f32_e32 v71, v215, v187
	v_exp_f32_e32 v68, v68
	v_exp_f32_e32 v69, v69
	v_fmac_f32_e32 v70, 0x3e38aa3b, v91
	v_fmac_f32_e32 v71, 0x3e38aa3b, v75
	v_exp_f32_e32 v70, v70
	v_exp_f32_e32 v71, v71
	v_sub_f32_e32 v74, v66, v67
	v_pk_mul_f32 v[66:67], v[224:225], v[68:69]
	v_sub_f32_e32 v68, v216, v186
	v_sub_f32_e32 v69, v216, v187
	v_sub_f32_e32 v75, v66, v67
	v_pk_mul_f32 v[66:67], v[224:225], v[70:71]
	v_fmac_f32_e32 v68, 0x3e38aa3b, v92
	v_fmac_f32_e32 v69, 0x3e38aa3b, v76
	v_sub_f32_e32 v70, v217, v186
	v_sub_f32_e32 v71, v217, v187
	v_exp_f32_e32 v68, v68
	v_exp_f32_e32 v69, v69
	v_fmac_f32_e32 v70, 0x3e38aa3b, v93
	v_fmac_f32_e32 v71, 0x3e38aa3b, v77
	v_exp_f32_e32 v70, v70
	v_exp_f32_e32 v71, v71
	v_sub_f32_e32 v76, v66, v67
	v_pk_mul_f32 v[66:67], v[224:225], v[68:69]
	v_sub_f32_e32 v68, v218, v186
	v_sub_f32_e32 v69, v218, v187
	v_sub_f32_e32 v77, v66, v67
	v_pk_mul_f32 v[66:67], v[224:225], v[70:71]
	v_fmac_f32_e32 v68, 0x3e38aa3b, v94
	v_fmac_f32_e32 v69, 0x3e38aa3b, v78
	v_sub_f32_e32 v70, v219, v186
	v_sub_f32_e32 v71, v219, v187
	v_exp_f32_e32 v68, v68
	v_exp_f32_e32 v69, v69
	v_fmac_f32_e32 v70, 0x3e38aa3b, v95
	v_fmac_f32_e32 v71, 0x3e38aa3b, v79
	v_exp_f32_e32 v70, v70
	v_exp_f32_e32 v71, v71
	v_sub_f32_e32 v78, v66, v67
	v_pk_mul_f32 v[66:67], v[224:225], v[68:69]
	v_sub_f32_e32 v68, v220, v186
	v_sub_f32_e32 v69, v220, v187
	v_sub_f32_e32 v79, v66, v67
	v_pk_mul_f32 v[66:67], v[224:225], v[70:71]
	v_fmac_f32_e32 v68, 0x3e38aa3b, v96
	v_fmac_f32_e32 v69, 0x3e38aa3b, v80
	v_sub_f32_e32 v70, v221, v186
	v_sub_f32_e32 v71, v221, v187
	v_exp_f32_e32 v68, v68
	v_exp_f32_e32 v69, v69
	v_fmac_f32_e32 v70, 0x3e38aa3b, v97
	v_fmac_f32_e32 v71, 0x3e38aa3b, v81
	v_exp_f32_e32 v70, v70
	v_exp_f32_e32 v71, v71
	v_sub_f32_e32 v80, v66, v67
	v_pk_mul_f32 v[66:67], v[224:225], v[68:69]
	s_nop 0
	v_sub_f32_e32 v81, v66, v67
	v_pk_mul_f32 v[66:67], v[224:225], v[70:71]
	s_nop 0
	v_sub_f32_e32 v86, v66, v67
	v_cvt_pk_bf16_f32 v66, v184, v84
	v_cvt_pk_bf16_f32 v67, v82, v83
	v_cvt_pk_bf16_f32 v68, v85, v72
	v_cvt_pk_bf16_f32 v69, v73, v74
	v_cvt_pk_bf16_f32 v70, v75, v76
	v_cvt_pk_bf16_f32 v71, v77, v78
	v_cvt_pk_bf16_f32 v72, v79, v80
	v_cvt_pk_bf16_f32 v73, v81, v86
	ds_read_b64_tr_b16 v[78:79], v232 offset:5248
	ds_read_b64_tr_b16 v[80:81], v232 offset:7808
	ds_read_b64_tr_b16 v[82:83], v232 offset:192
	ds_read_b64_tr_b16 v[84:85], v232 offset:2752
	ds_read_b64_tr_b16 v[86:87], v232 offset:5312
	ds_read_b64_tr_b16 v[88:89], v232 offset:7872
	s_setprio 1
	s_waitcnt lgkmcnt(6)
	v_mfma_f32_32x32x16_bf16 v[50:65], v[134:137], v[66:69], v[50:65]
	v_mfma_f32_32x32x16_bf16 v[50:65], v[138:141], v[70:73], v[50:65]
	v_mfma_f32_32x32x16_bf16 v[34:49], v[142:145], v[66:69], v[34:49]
	v_mfma_f32_32x32x16_bf16 v[34:49], v[146:149], v[70:73], v[34:49]
	v_mfma_f32_32x32x16_bf16 v[18:33], v[150:153], v[66:69], v[18:33]
	s_waitcnt lgkmcnt(4)
	v_mfma_f32_32x32x16_bf16 v[18:33], v[78:81], v[70:73], v[18:33]
	s_waitcnt lgkmcnt(2)
	v_mfma_f32_32x32x16_bf16 v[2:17], v[82:85], v[66:69], v[2:17]
	s_waitcnt lgkmcnt(0)
	v_mfma_f32_32x32x16_bf16 v[2:17], v[86:89], v[70:73], v[2:17]
	s_setprio 0
	s_cmp_lg_u32 s22, s0
	v_add_f32_e32 v231, v226, v231
	s_barrier
	s_waitcnt vmcnt(1)
	ds_write_b128 v154, v[130:133] offset:10240
	ds_write_b128 v154, v[130:133] offset:29184
	ds_write_b128 v154, v[130:133] offset:48128
	ds_write_b128 v155, v[130:133] offset:10240
	ds_write_b128 v155, v[130:133] offset:29184
	ds_write_b128 v155, v[130:133] offset:48128
	ds_write_b128 v156, v[130:133] offset:10240
	ds_write_b128 v156, v[130:133] offset:29184
	s_waitcnt vmcnt(0)
	ds_write_b128 v157, v[234:237]
	ds_write_b128 v157, v[234:237] offset:18944
	ds_write_b128 v157, v[234:237] offset:37888
	ds_write_b128 v157, v[234:237] offset:56832
	ds_write_b128 v160, v[234:237]
	ds_write_b128 v160, v[234:237] offset:18944
	ds_write_b128 v160, v[234:237] offset:37888
	ds_write_b128 v160, v[234:237] offset:56832
	s_waitcnt lgkmcnt(0)
	s_barrier
	s_cbranch_scc0 .LBB0_328
; #define MFMA32(a, b, c) __builtin_amdgcn_mfma_f32_32x32x16_bf16((a), (b), (c), 0, 0, 0)
; __device__ __forceinline__ int crow(int r, int hi) { return (r & 3) + 8 * (r >> 2) + 4 * hi; }
; __device__ __forceinline__ void diff_task(const bf16_t* proj, bf16_t* xo, int b, int h, int qb, float lam, float post, const float* g_diff, int  , LAS unsigned char* vl) {
;     ...
;         read_kf(kf, klane);
;         f32x16 s0 = {}, s1 = {};
; #pragma unroll
;         for (int d0 = 0; d0 < 4; ++d0) { s0 = MFMA32(kf[d0], qf[d0], s0); s1 = MFMA32(kf[4 + d0], qf[4 + d0], s1); }
;         const int kn = kc < qb ? kc + 1 : kc;
;         load_v(kr, kcol + (size_t)(kn * 32) * NIN, 1, voff);
;         if (kc == qb) {
; #pragma unroll
;             for (int r = 0; r < 16; ++r) if (crow(r, hi) > r32) { s0[r] = NEGBIG; s1[r] = NEGBIG; }
;         }
;         const float e0 = m0 - sh, e1 = m1 - sh;
;         float p[16];
; #pragma unroll
;         for (int r = 0; r < 16; ++r) { const float bq0 = B0(r) - e0, bq1 = B0(r) - e1; p[r] = __builtin_amdgcn_exp2f(s0[r] * c1 + bq0) * i0 - __builtin_amdgcn_exp2f(s1[r] * c1 + bq1) * i1; }
;         bf16x8 pf0 = pack8(p), pf1 = pack8(p + 8);
;         asm volatile("" : "+v"(pf0), "+v"(pf1));
;         load_v(vr, vcol + (size_t)(kn * 32) * NIN, 1, voff);
.LBB0_326:
	ds_read_b128 v[66:69], v228 offset:10240
	ds_read_b128 v[130:133], v228 offset:10272
	ds_read_b128 v[134:137], v228 offset:10304
	ds_read_b128 v[138:141], v228 offset:10336
	ds_read_b128 v[70:73], v228 offset:10368
	ds_read_b128 v[142:145], v228 offset:10400
	ds_read_b128 v[146:149], v228 offset:10432
	ds_read_b128 v[150:153], v228 offset:10464
	s_waitcnt lgkmcnt(7)
	v_mfma_f32_32x32x16_bf16 v[82:97], v[66:69], v[98:101], 0
	s_mov_b32 s1, s0
	s_add_i32 s0, s0, 1
	s_cmp_lt_u32 s0, s22
	s_cselect_b32 s2, s0, s1
	s_lshl_b32 s3, s2, 5
	s_mul_i32 s2, s2, 0x30000
	s_mul_hi_u32 s3, s3, 0x1800
	s_waitcnt lgkmcnt(3)
	v_mfma_f32_32x32x16_bf16 v[66:81], v[70:73], v[114:117], 0
	v_lshl_add_u64 v[158:159], s[2:3], 1, v[204:205]
	s_cmp_lg_u32 s19, s1
	v_mfma_f32_32x32x16_bf16 v[82:97], v[130:133], v[102:105], v[82:97]
	v_add_co_u32_e32 v158, vcc, s81, v158
	s_waitcnt lgkmcnt(2)
	v_mfma_f32_32x32x16_bf16 v[66:81], v[142:145], v[118:121], v[66:81]
	v_mfma_f32_32x32x16_bf16 v[82:97], v[134:137], v[106:109], v[82:97]
	v_addc_co_u32_e32 v159, vcc, 0, v159, vcc
	global_load_dwordx4 v[130:133], v[158:159], off
	v_lshl_add_u64 v[238:239], s[2:3], 1, v[222:223]
	v_add_co_u32_e32 v238, vcc, s81, v238
	s_nop 1
	v_addc_co_u32_e32 v239, vcc, 0, v239, vcc
	global_load_dwordx4 v[234:237], v[238:239], off
	s_waitcnt lgkmcnt(1)
	v_mfma_f32_32x32x16_bf16 v[66:81], v[146:149], v[122:125], v[66:81]
	v_mfma_f32_32x32x16_bf16 v[82:97], v[138:141], v[110:113], v[82:97]
	s_waitcnt lgkmcnt(0)
	v_mfma_f32_32x32x16_bf16 v[66:81], v[150:153], v[126:129], v[66:81]
	s_nop 7
	s_nop 3
	s_cbranch_scc1 .Lpb1_chk
	v_cndmask_b32_e64 v184, v82, v248, s[38:39]
	v_cndmask_b32_e64 v185, v66, v248, s[38:39]
	v_cndmask_b32_e64 v83, v248, v83, s[42:43]
	v_cndmask_b32_e64 v82, v184, v82, s[42:43]
	v_cndmask_b32_e64 v67, v248, v67, s[42:43]
	v_cndmask_b32_e64 v66, v185, v66, s[42:43]
	v_cndmask_b32_e64 v84, v84, v248, s[44:45]
	v_cndmask_b32_e64 v68, v68, v248, s[44:45]
	v_cndmask_b32_e64 v85, v85, v248, s[46:47]
	v_cndmask_b32_e64 v69, v69, v248, s[46:47]
	v_cndmask_b32_e64 v86, v86, v248, s[48:49]
	v_cndmask_b32_e64 v70, v70, v248, s[48:49]
	v_cndmask_b32_e64 v87, v87, v248, s[50:51]
	v_cndmask_b32_e64 v71, v71, v248, s[50:51]
	v_cndmask_b32_e64 v88, v88, v248, s[52:53]
	v_cndmask_b32_e64 v72, v72, v248, s[52:53]
	v_cndmask_b32_e64 v89, v89, v248, s[54:55]
	v_cndmask_b32_e64 v73, v73, v248, s[54:55]
	v_cndmask_b32_e64 v90, v90, v248, s[56:57]
	v_cndmask_b32_e64 v74, v74, v248, s[56:57]
	v_cndmask_b32_e64 v91, v91, v248, s[58:59]
	v_cndmask_b32_e64 v75, v75, v248, s[58:59]
	v_cndmask_b32_e64 v92, v92, v248, s[60:61]
	v_cndmask_b32_e64 v76, v76, v248, s[60:61]
	v_cndmask_b32_e64 v93, v93, v248, s[62:63]
	v_cndmask_b32_e64 v77, v77, v248, s[62:63]
	v_cndmask_b32_e64 v94, v94, v248, s[64:65]
	v_cndmask_b32_e64 v78, v78, v248, s[64:65]
	v_cndmask_b32_e64 v95, v95, v248, s[66:67]
	v_cndmask_b32_e64 v79, v79, v248, s[66:67]
	v_cndmask_b32_e64 v96, v96, v248, s[68:69]
	v_cndmask_b32_e64 v80, v80, v248, s[68:69]
	v_cndmask_b32_e64 v97, v97, v248, s[70:71]
	v_cndmask_b32_e64 v81, v81, v248, s[70:71]
	s_branch .LBB0_325

; #define LAS __attribute__((address_space(3)))
; #define MFMA32(a, b, c) __builtin_amdgcn_mfma_f32_32x32x16_bf16((a), (b), (c), 0, 0, 0)
; __device__ __forceinline__ s16x4 vtr(const LAS unsigned char* p) { return __builtin_bit_cast(s16x4, __builtin_amdgcn_ds_read_tr16_b64_v4i16((LAS s16x4*)p)); }
; __device__ __forceinline__ void pv_chunk(f32x16 (&ot)[4], const LAS unsigned char* vtb, bf16x8 pf0, bf16x8 pf1) {
; #pragma unroll
;     for (int db = 0; db < 4; ++db)
; #pragma unroll
;         for (int s = 0; s < 2; ++s) {
;             const s16x4 a = vtr(vtb + (16 * s) * VROWB + 64 * db), b2 = vtr(vtb + (16 * s + 8) * VROWB + 64 * db);
;             const bf16x8 vf = (bf16x8){a[0], a[1], a[2], a[3], b2[0], b2[1], b2[2], b2[3]};
;             __builtin_amdgcn_s_setprio(1); ot[db] = MFMA32(vf, s ? pf1 : pf0, ot[db]); __builtin_amdgcn_s_setprio(0);
;         }
; __device__ __forceinline__ void diff_task(const bf16_t* proj, bf16_t* xo, int b, int h, int qb, float lam, float post, const float* g_diff, int  , LAS unsigned char* vl) {
;     ...
;         const float e0 = m0 - sh, e1 = m1 - sh;
;         float p[16];
; #pragma unroll
;         for (int r = 0; r < 16; ++r) { const float bq0 = B0(r) - e0, bq1 = B0(r) - e1; p[r] = __builtin_amdgcn_exp2f(s0[r] * c1 + bq0) * i0 - __builtin_amdgcn_exp2f(s1[r] * c1 + bq1) * i1; }
;         bf16x8 pf0 = pack8(p), pf1 = pack8(p + 8);
;         asm volatile("" : "+v"(pf0), "+v"(pf1));
;         load_v(vr, vcol + (size_t)(kn * 32) * NIN, 1, voff);
;         pv_chunk(ot, vtb, pf0, pf1);
;         store_k(kl, kr, lane);
;         store_v(vl, vr, lane);
;         sh += c2s;
;     }
.LBB0_339:
	ds_read_b64_tr_b16 v[134:135], v215
	ds_read_b64_tr_b16 v[136:137], v215 offset:2560
	ds_read_b64_tr_b16 v[138:139], v215 offset:5120
	ds_read_b64_tr_b16 v[140:141], v215 offset:7680
	ds_read_b64_tr_b16 v[142:143], v215 offset:64
	ds_read_b64_tr_b16 v[144:145], v215 offset:2624
	ds_read_b64_tr_b16 v[146:147], v215 offset:5184
	ds_read_b64_tr_b16 v[148:149], v215 offset:7744
	ds_read_b64_tr_b16 v[150:151], v215 offset:128
	ds_read_b64_tr_b16 v[152:153], v215 offset:2688
	v_sub_f32_e32 v186, v213, v0
	v_sub_f32_e32 v187, v214, v0
	v_sub_f32_e32 v184, v168, v186
	v_sub_f32_e32 v185, v168, v187
	v_fmac_f32_e32 v184, 0x3e38aa3b, v82
	v_fmac_f32_e32 v185, 0x3e38aa3b, v66
	v_exp_f32_e32 v184, v184
	v_exp_f32_e32 v185, v185
	v_sub_f32_e32 v82, v169, v187
	v_sub_f32_e32 v66, v169, v186
	v_fmac_f32_e32 v82, 0x3e38aa3b, v67
	v_fmac_f32_e32 v66, 0x3e38aa3b, v83
	v_exp_f32_e32 v67, v82
	v_pk_mul_f32 v[82:83], v[206:207], v[184:185]
	v_exp_f32_e32 v66, v66
	v_sub_f32_e32 v184, v82, v83
	v_sub_f32_e32 v82, v170, v186
	v_sub_f32_e32 v83, v170, v187
	v_fmac_f32_e32 v82, 0x3e38aa3b, v84
	v_fmac_f32_e32 v83, 0x3e38aa3b, v68
	v_sub_f32_e32 v68, v171, v186
	v_sub_f32_e32 v84, v171, v187
	v_exp_f32_e32 v82, v82
	v_exp_f32_e32 v83, v83
	v_fmac_f32_e32 v68, 0x3e38aa3b, v85
	v_fmac_f32_e32 v84, 0x3e38aa3b, v69
	v_exp_f32_e32 v68, v68
	v_exp_f32_e32 v69, v84
	v_pk_mul_f32 v[66:67], v[206:207], v[66:67]
	s_nop 0
	v_sub_f32_e32 v84, v66, v67
	v_pk_mul_f32 v[66:67], v[206:207], v[82:83]
	v_sub_f32_e32 v83, v173, v187
	v_sub_f32_e32 v82, v66, v67
	v_pk_mul_f32 v[66:67], v[206:207], v[68:69]
	v_sub_f32_e32 v68, v172, v186
	v_sub_f32_e32 v69, v172, v187
	v_fmac_f32_e32 v68, 0x3e38aa3b, v86
	v_fmac_f32_e32 v69, 0x3e38aa3b, v70
	v_sub_f32_e32 v70, v173, v186
	v_exp_f32_e32 v68, v68
	v_exp_f32_e32 v69, v69
	v_fmac_f32_e32 v70, 0x3e38aa3b, v87
	v_fmac_f32_e32 v83, 0x3e38aa3b, v71
	v_exp_f32_e32 v70, v70
	v_exp_f32_e32 v71, v83
	v_sub_f32_e32 v83, v66, v67
	v_pk_mul_f32 v[66:67], v[206:207], v[68:69]
	v_sub_f32_e32 v68, v174, v186
	v_sub_f32_e32 v69, v174, v187
	v_sub_f32_e32 v85, v66, v67
	v_pk_mul_f32 v[66:67], v[206:207], v[70:71]
	v_fmac_f32_e32 v68, 0x3e38aa3b, v88
	v_fmac_f32_e32 v69, 0x3e38aa3b, v72
	v_sub_f32_e32 v70, v175, v186
	v_sub_f32_e32 v71, v175, v187
	v_exp_f32_e32 v68, v68
	v_exp_f32_e32 v69, v69
	v_fmac_f32_e32 v70, 0x3e38aa3b, v89
	v_fmac_f32_e32 v71, 0x3e38aa3b, v73
	v_exp_f32_e32 v70, v70
	v_exp_f32_e32 v71, v71
	v_sub_f32_e32 v72, v66, v67
	v_pk_mul_f32 v[66:67], v[206:207], v[68:69]
	v_sub_f32_e32 v68, v176, v186
	v_sub_f32_e32 v69, v176, v187
	v_sub_f32_e32 v73, v66, v67
	v_pk_mul_f32 v[66:67], v[206:207], v[70:71]
	v_fmac_f32_e32 v68, 0x3e38aa3b, v90
	v_fmac_f32_e32 v69, 0x3e38aa3b, v74
	v_sub_f32_e32 v70, v177, v186
	v_sub_f32_e32 v71, v177, v187
	v_exp_f32_e32 v68, v68
	v_exp_f32_e32 v69, v69
	v_fmac_f32_e32 v70, 0x3e38aa3b, v91
	v_fmac_f32_e32 v71, 0x3e38aa3b, v75
	v_exp_f32_e32 v70, v70
	v_exp_f32_e32 v71, v71
	v_sub_f32_e32 v74, v66, v67
	v_pk_mul_f32 v[66:67], v[206:207], v[68:69]
	v_sub_f32_e32 v68, v198, v186
	v_sub_f32_e32 v69, v198, v187
	v_sub_f32_e32 v75, v66, v67
	v_pk_mul_f32 v[66:67], v[206:207], v[70:71]
	v_fmac_f32_e32 v68, 0x3e38aa3b, v92
	v_fmac_f32_e32 v69, 0x3e38aa3b, v76
	v_sub_f32_e32 v70, v199, v186
	v_sub_f32_e32 v71, v199, v187
	v_exp_f32_e32 v68, v68
	v_exp_f32_e32 v69, v69
	v_fmac_f32_e32 v70, 0x3e38aa3b, v93
	v_fmac_f32_e32 v71, 0x3e38aa3b, v77
	v_exp_f32_e32 v70, v70
	v_exp_f32_e32 v71, v71
	v_sub_f32_e32 v76, v66, v67
	v_pk_mul_f32 v[66:67], v[206:207], v[68:69]
	v_sub_f32_e32 v68, v200, v186
	v_sub_f32_e32 v69, v200, v187
	v_sub_f32_e32 v77, v66, v67
	v_pk_mul_f32 v[66:67], v[206:207], v[70:71]
	v_fmac_f32_e32 v68, 0x3e38aa3b, v94
	v_fmac_f32_e32 v69, 0x3e38aa3b, v78
	v_sub_f32_e32 v70, v201, v186
	v_sub_f32_e32 v71, v201, v187
	v_exp_f32_e32 v68, v68
	v_exp_f32_e32 v69, v69
	v_fmac_f32_e32 v70, 0x3e38aa3b, v95
	v_fmac_f32_e32 v71, 0x3e38aa3b, v79
	v_exp_f32_e32 v70, v70
	v_exp_f32_e32 v71, v71
	v_sub_f32_e32 v78, v66, v67
	v_pk_mul_f32 v[66:67], v[206:207], v[68:69]
	v_sub_f32_e32 v68, v202, v186
	v_sub_f32_e32 v69, v202, v187
	v_sub_f32_e32 v79, v66, v67
	v_pk_mul_f32 v[66:67], v[206:207], v[70:71]
	v_fmac_f32_e32 v68, 0x3e38aa3b, v96
	v_fmac_f32_e32 v69, 0x3e38aa3b, v80
	v_sub_f32_e32 v70, v203, v186
	v_sub_f32_e32 v71, v203, v187
	v_exp_f32_e32 v68, v68
	v_exp_f32_e32 v69, v69
	v_fmac_f32_e32 v70, 0x3e38aa3b, v97
	v_fmac_f32_e32 v71, 0x3e38aa3b, v81
	v_exp_f32_e32 v70, v70
	v_exp_f32_e32 v71, v71
	v_sub_f32_e32 v80, v66, v67
	v_pk_mul_f32 v[66:67], v[206:207], v[68:69]
	s_nop 0
	v_sub_f32_e32 v81, v66, v67
	v_pk_mul_f32 v[66:67], v[206:207], v[70:71]
	s_nop 0
	v_sub_f32_e32 v86, v66, v67
	v_cvt_pk_bf16_f32 v66, v184, v84
	v_cvt_pk_bf16_f32 v67, v82, v83
	v_cvt_pk_bf16_f32 v68, v85, v72
	v_cvt_pk_bf16_f32 v69, v73, v74
	v_cvt_pk_bf16_f32 v70, v75, v76
	v_cvt_pk_bf16_f32 v71, v77, v78
	v_cvt_pk_bf16_f32 v72, v79, v80
	v_cvt_pk_bf16_f32 v73, v81, v86
	ds_read_b64_tr_b16 v[78:79], v215 offset:5248
	ds_read_b64_tr_b16 v[80:81], v215 offset:7808
	ds_read_b64_tr_b16 v[82:83], v215 offset:192
	ds_read_b64_tr_b16 v[84:85], v215 offset:2752
	ds_read_b64_tr_b16 v[86:87], v215 offset:5312
	ds_read_b64_tr_b16 v[88:89], v215 offset:7872
	s_setprio 1
	s_waitcnt lgkmcnt(6)
	v_mfma_f32_32x32x16_bf16 v[50:65], v[134:137], v[66:69], v[50:65]
	v_mfma_f32_32x32x16_bf16 v[50:65], v[138:141], v[70:73], v[50:65]
	v_mfma_f32_32x32x16_bf16 v[34:49], v[142:145], v[66:69], v[34:49]
	v_mfma_f32_32x32x16_bf16 v[34:49], v[146:149], v[70:73], v[34:49]
	v_mfma_f32_32x32x16_bf16 v[18:33], v[150:153], v[66:69], v[18:33]
	s_waitcnt lgkmcnt(4)
	v_mfma_f32_32x32x16_bf16 v[18:33], v[78:81], v[70:73], v[18:33]
	s_waitcnt lgkmcnt(2)
	v_mfma_f32_32x32x16_bf16 v[2:17], v[82:85], v[66:69], v[2:17]
	s_waitcnt lgkmcnt(0)
	v_mfma_f32_32x32x16_bf16 v[2:17], v[86:89], v[70:73], v[2:17]
	s_setprio 0
	s_cmp_lg_u32 s1, s0
	v_add_f32_e32 v0, v226, v0
	s_barrier
	s_waitcnt vmcnt(1)
	ds_write_b128 v154, v[130:133] offset:10240
	ds_write_b128 v154, v[130:133] offset:29184
	ds_write_b128 v154, v[130:133] offset:48128
	ds_write_b128 v155, v[130:133] offset:10240
	ds_write_b128 v155, v[130:133] offset:29184
	ds_write_b128 v155, v[130:133] offset:48128
	ds_write_b128 v156, v[130:133] offset:10240
	ds_write_b128 v156, v[130:133] offset:29184
	s_waitcnt vmcnt(0)
	ds_write_b128 v157, v[234:237]
	ds_write_b128 v157, v[234:237] offset:18944
	ds_write_b128 v157, v[234:237] offset:37888
	ds_write_b128 v157, v[234:237] offset:56832
	ds_write_b128 v160, v[234:237]
	ds_write_b128 v160, v[234:237] offset:18944
	ds_write_b128 v160, v[234:237] offset:37888
	ds_write_b128 v160, v[234:237] offset:56832
	s_waitcnt lgkmcnt(0)
	s_barrier
	s_cbranch_scc0 .LBB0_313
; #define MFMA32(a, b, c) __builtin_amdgcn_mfma_f32_32x32x16_bf16((a), (b), (c), 0, 0, 0)
; __device__ __forceinline__ int crow(int r, int hi) { return (r & 3) + 8 * (r >> 2) + 4 * hi; }
; __device__ __forceinline__ void diff_task(const bf16_t* proj, bf16_t* xo, int b, int h, int qb, float lam, float post, const float* g_diff, int  , LAS unsigned char* vl) {
;     ...
;         read_kf(kf, klane);
;         f32x16 s0 = {}, s1 = {};
; #pragma unroll
;         for (int d0 = 0; d0 < 4; ++d0) { s0 = MFMA32(kf[d0], qf[d0], s0); s1 = MFMA32(kf[4 + d0], qf[4 + d0], s1); }
;         const int kn = kc < qb ? kc + 1 : kc;
;         load_v(kr, kcol + (size_t)(kn * 32) * NIN, 1, voff);
;         if (kc == qb) {
; #pragma unroll
;             for (int r = 0; r < 16; ++r) if (crow(r, hi) > r32) { s0[r] = NEGBIG; s1[r] = NEGBIG; }
;         }
;         const float e0 = m0 - sh, e1 = m1 - sh;
;         float p[16];
; #pragma unroll
;         for (int r = 0; r < 16; ++r) { const float bq0 = B0(r) - e0, bq1 = B0(r) - e1; p[r] = __builtin_amdgcn_exp2f(s0[r] * c1 + bq0) * i0 - __builtin_amdgcn_exp2f(s1[r] * c1 + bq1) * i1; }
;         bf16x8 pf0 = pack8(p), pf1 = pack8(p + 8);
;         asm volatile("" : "+v"(pf0), "+v"(pf1));
;         load_v(vr, vcol + (size_t)(kn * 32) * NIN, 1, voff);
.LBB0_340:
	ds_read_b128 v[66:69], v211 offset:10240
	ds_read_b128 v[130:133], v211 offset:10272
	ds_read_b128 v[134:137], v211 offset:10304
	ds_read_b128 v[138:141], v211 offset:10336
	ds_read_b128 v[70:73], v211 offset:10368
	ds_read_b128 v[142:145], v211 offset:10400
	ds_read_b128 v[146:149], v211 offset:10432
	ds_read_b128 v[150:153], v211 offset:10464
	s_waitcnt lgkmcnt(7)
	v_mfma_f32_32x32x16_bf16 v[82:97], v[66:69], v[98:101], 0
	s_mov_b32 s5, s0
	s_add_i32 s0, s0, 1
	s_cmp_lt_u32 s0, s1
	s_cselect_b32 s2, s0, s5
	s_lshl_b32 s3, s2, 5
	s_mul_i32 s2, s2, 0x30000
	s_mul_hi_u32 s3, s3, 0x1800
	s_waitcnt lgkmcnt(3)
	v_mfma_f32_32x32x16_bf16 v[66:81], v[70:73], v[114:117], 0
	v_lshl_add_u64 v[158:159], s[2:3], 1, v[204:205]
	s_cmp_lg_u32 s4, s5
	v_mfma_f32_32x32x16_bf16 v[82:97], v[130:133], v[102:105], v[82:97]
	v_add_co_u32_e32 v158, vcc, s81, v158
	s_waitcnt lgkmcnt(2)
	v_mfma_f32_32x32x16_bf16 v[66:81], v[142:145], v[118:121], v[66:81]
	v_mfma_f32_32x32x16_bf16 v[82:97], v[134:137], v[106:109], v[82:97]
	v_addc_co_u32_e32 v159, vcc, 0, v159, vcc
	global_load_dwordx4 v[130:133], v[158:159], off
	v_lshl_add_u64 v[238:239], s[2:3], 1, v[208:209]
	v_add_co_u32_e32 v238, vcc, s81, v238
	s_nop 1
	v_addc_co_u32_e32 v239, vcc, 0, v239, vcc
	global_load_dwordx4 v[234:237], v[238:239], off
	s_waitcnt lgkmcnt(1)
	v_mfma_f32_32x32x16_bf16 v[66:81], v[146:149], v[122:125], v[66:81]
	v_mfma_f32_32x32x16_bf16 v[82:97], v[138:141], v[110:113], v[82:97]
	s_waitcnt lgkmcnt(0)
	v_mfma_f32_32x32x16_bf16 v[66:81], v[150:153], v[126:129], v[66:81]
	s_nop 7
	s_nop 3
	s_cbranch_scc1 .Lpb2_chk
	v_cndmask_b32_e64 v184, v82, v248, s[38:39]
	v_cndmask_b32_e64 v185, v66, v248, s[38:39]
	v_cndmask_b32_e64 v83, v248, v83, s[42:43]
	v_cndmask_b32_e64 v82, v184, v82, s[42:43]
	v_cndmask_b32_e64 v67, v248, v67, s[42:43]
	v_cndmask_b32_e64 v66, v185, v66, s[42:43]
	v_cndmask_b32_e64 v84, v84, v248, s[44:45]
	v_cndmask_b32_e64 v68, v68, v248, s[44:45]
	v_cndmask_b32_e64 v85, v85, v248, s[46:47]
	v_cndmask_b32_e64 v69, v69, v248, s[46:47]
	v_cndmask_b32_e64 v86, v86, v248, s[48:49]
	v_cndmask_b32_e64 v70, v70, v248, s[48:49]
	v_cndmask_b32_e64 v87, v87, v248, s[50:51]
	v_cndmask_b32_e64 v71, v71, v248, s[50:51]
	v_cndmask_b32_e64 v88, v88, v248, s[52:53]
	v_cndmask_b32_e64 v72, v72, v248, s[52:53]
	v_cndmask_b32_e64 v89, v89, v248, s[54:55]
	v_cndmask_b32_e64 v73, v73, v248, s[54:55]
	v_cndmask_b32_e64 v90, v90, v248, s[56:57]
	v_cndmask_b32_e64 v74, v74, v248, s[56:57]
	v_cndmask_b32_e64 v91, v91, v248, s[58:59]
	v_cndmask_b32_e64 v75, v75, v248, s[58:59]
	v_cndmask_b32_e64 v92, v92, v248, s[60:61]
	v_cndmask_b32_e64 v76, v76, v248, s[60:61]
	v_cndmask_b32_e64 v93, v93, v248, s[62:63]
	v_cndmask_b32_e64 v77, v77, v248, s[62:63]
	v_cndmask_b32_e64 v94, v94, v248, s[64:65]
	v_cndmask_b32_e64 v78, v78, v248, s[64:65]
	v_cndmask_b32_e64 v95, v95, v248, s[66:67]
	v_cndmask_b32_e64 v79, v79, v248, s[66:67]
	v_cndmask_b32_e64 v96, v96, v248, s[68:69]
	v_cndmask_b32_e64 v80, v80, v248, s[68:69]
	v_cndmask_b32_e64 v97, v97, v248, s[70:71]
	v_cndmask_b32_e64 v81, v81, v248, s[70:71]
	s_branch .LBB0_339
